# up-projection epilogue: counted waits so the next conv-weight group stays in flight
# baseline (speedup 1.0000x reference)
.LBB0_1433:
	s_or_b64 exec, exec, s[6:7]
	v_or_b32_e32 v132, 4, v188
	v_ashrrev_i32_e32 v133, 31, v132
	v_lshlrev_b64 v[136:137], 2, v[132:133]
	s_waitcnt lgkmcnt(0)
	s_barrier
	v_lshl_add_u64 v[132:133], s[18:19], 0, v[136:137]
	v_lshl_add_u64 v[136:137], s[20:21], 0, v[136:137]
	global_load_dwordx4 v[128:131], v[212:213], off offset:16
	v_lshlrev_b32_e32 v247, 2, v167
	global_load_dwordx4 v[132:135], v[132:133], off
	s_nop 0
	global_load_dwordx4 v[136:139], v[136:137], off
	s_nop 0
	global_load_dwordx4 v[140:143], v[206:207], off offset:16
	v_readlane_b32 s10, v254, 60
	v_cmp_eq_u32_e64 s[6:7], 15, v242
	v_cmp_eq_u32_e32 vcc, 0, v242
	v_add_u32_e32 v167, s10, v247
	ds_read_b128 v[190:193], v167
	v_readlane_b32 s10, v254, 63
	v_mov_b32_e32 v169, v168
	v_mov_b32_e32 v179, v178
	v_add_u32_e32 v244, s10, v247
	ds_read_b128 v[194:197], v244 offset:2048
	s_waitcnt lgkmcnt(0)
	v_pk_mul_f32 v[190:191], v[170:171], v[190:191]
	v_mov_b32_e32 v167, v166
	v_cndmask_b32_e64 v175, v116, v190, s[6:7]
	v_pk_mul_f32 v[192:193], v[166:167], v[192:193]
	v_pk_mul_f32 v[222:223], v[172:173], v[194:195]
	v_mov_b32_dpp v190, v175 row_ror:1 row_mask:0xf bank_mask:0xf
	v_cndmask_b32_e32 v175, v116, v124, vcc
	v_pk_mul_f32 v[220:221], v[168:169], v[196:197]
	v_readlane_b32 s10, v255, 0
	v_mov_b32_dpp v194, v175 row_ror:15 row_mask:0xf bank_mask:0xf
	v_cndmask_b32_e64 v175, v117, v191, s[6:7]
	s_movk_i32 s23, 0x5000
	v_add_u32_e32 v246, s73, v247
	v_mov_b32_dpp v191, v175 row_ror:1 row_mask:0xf bank_mask:0xf
	v_cndmask_b32_e32 v175, v117, v125, vcc
	v_add_u32_e32 v245, s94, v247
	s_nop 0
	v_mov_b32_dpp v195, v175 row_ror:15 row_mask:0xf bank_mask:0xf
	v_cndmask_b32_e64 v175, v118, v192, s[6:7]
	s_waitcnt vmcnt(4)
	v_pk_fma_f32 v[194:195], v[152:153], v[194:195], v[156:157]
	v_mov_b32_dpp v192, v175 row_ror:1 row_mask:0xf bank_mask:0xf
	v_cndmask_b32_e32 v175, v118, v126, vcc
	v_pk_fma_f32 v[194:195], v[148:149], v[116:117], v[194:195]
	v_cndmask_b32_e64 v116, v124, v116, s[6:7]
	v_mov_b32_dpp v196, v175 row_ror:15 row_mask:0xf bank_mask:0xf
	v_cndmask_b32_e64 v175, v119, v193, s[6:7]
	v_pk_fma_f32 v[204:205], v[144:145], v[190:191], v[194:195]
	v_cndmask_b32_e64 v117, v125, v117, s[6:7]
	v_mov_b32_dpp v193, v175 row_ror:1 row_mask:0xf bank_mask:0xf
	v_cndmask_b32_e32 v175, v119, v127, vcc
	v_mov_b32_dpp v116, v116 row_ror:1 row_mask:0xf bank_mask:0xf
	v_mov_b32_dpp v117, v117 row_ror:1 row_mask:0xf bank_mask:0xf
	v_mov_b32_dpp v197, v175 row_ror:15 row_mask:0xf bank_mask:0xf
	v_cndmask_b32_e32 v175, v124, v120, vcc
	v_pk_fma_f32 v[196:197], v[154:155], v[196:197], v[158:159]
	s_nop 0
	v_mov_b32_dpp v190, v175 row_ror:15 row_mask:0xf bank_mask:0xf
	v_cndmask_b32_e32 v175, v125, v121, vcc
	v_pk_fma_f32 v[196:197], v[150:151], v[118:119], v[196:197]
	v_cndmask_b32_e64 v118, v126, v118, s[6:7]
	v_mov_b32_dpp v191, v175 row_ror:15 row_mask:0xf bank_mask:0xf
	v_cndmask_b32_e32 v175, v126, v122, vcc
	v_pk_fma_f32 v[202:203], v[146:147], v[192:193], v[196:197]
	v_cndmask_b32_e64 v119, v127, v119, s[6:7]
	v_mov_b32_dpp v192, v175 row_ror:15 row_mask:0xf bank_mask:0xf
	v_cndmask_b32_e32 v175, v127, v123, vcc
	v_pk_fma_f32 v[190:191], v[152:153], v[190:191], v[156:157]
	v_mov_b32_dpp v118, v118 row_ror:1 row_mask:0xf bank_mask:0xf
	v_mov_b32_dpp v193, v175 row_ror:15 row_mask:0xf bank_mask:0xf
	v_pk_fma_f32 v[192:193], v[154:155], v[192:193], v[158:159]
	v_mov_b32_dpp v119, v119 row_ror:1 row_mask:0xf bank_mask:0xf
	v_pk_fma_f32 v[190:191], v[148:149], v[124:125], v[190:191]
	v_pk_fma_f32 v[192:193], v[150:151], v[126:127], v[192:193]
	v_pk_fma_f32 v[200:201], v[144:145], v[116:117], v[190:191]
	v_pk_fma_f32 v[198:199], v[146:147], v[118:119], v[192:193]
	v_cndmask_b32_e32 v117, v120, v112, vcc
	v_cndmask_b32_e32 v119, v121, v113, vcc
	v_cndmask_b32_e64 v116, v120, v124, s[6:7]
	v_mov_b32_dpp v118, v117 row_ror:15 row_mask:0xf bank_mask:0xf
	v_mov_b32_dpp v119, v119 row_ror:15 row_mask:0xf bank_mask:0xf
	v_cndmask_b32_e64 v117, v121, v125, s[6:7]
	v_cndmask_b32_e32 v125, v122, v114, vcc
	v_pk_fma_f32 v[118:119], v[152:153], v[118:119], v[156:157]
	v_mov_b32_dpp v116, v116 row_ror:1 row_mask:0xf bank_mask:0xf
	v_mov_b32_dpp v117, v117 row_ror:1 row_mask:0xf bank_mask:0xf
	v_cndmask_b32_e64 v124, v122, v126, s[6:7]
	v_mov_b32_dpp v126, v125 row_ror:15 row_mask:0xf bank_mask:0xf
	v_cndmask_b32_e64 v125, v123, v127, s[6:7]
	v_cndmask_b32_e32 v127, v123, v115, vcc
	v_pk_fma_f32 v[118:119], v[148:149], v[120:121], v[118:119]
	v_mov_b32_e32 v175, v174
	v_mov_b32_dpp v127, v127 row_ror:15 row_mask:0xf bank_mask:0xf
	v_pk_fma_f32 v[196:197], v[144:145], v[116:117], v[118:119]
	v_cndmask_b32_e32 v117, v112, v222, vcc
	v_cndmask_b32_e32 v119, v113, v223, vcc
	v_pk_fma_f32 v[126:127], v[154:155], v[126:127], v[158:159]
	v_mov_b32_dpp v118, v117 row_ror:15 row_mask:0xf bank_mask:0xf
	v_cndmask_b32_e64 v117, v113, v121, s[6:7]
	v_mov_b32_dpp v119, v119 row_ror:15 row_mask:0xf bank_mask:0xf
	v_cndmask_b32_e32 v121, v114, v220, vcc
	v_pk_fma_f32 v[126:127], v[150:151], v[122:123], v[126:127]
	v_cndmask_b32_e64 v116, v112, v120, s[6:7]
	v_cndmask_b32_e64 v120, v114, v122, s[6:7]
	v_mov_b32_dpp v122, v121 row_ror:15 row_mask:0xf bank_mask:0xf
	v_cndmask_b32_e64 v121, v115, v123, s[6:7]
	v_cndmask_b32_e32 v123, v115, v221, vcc
	v_pk_fma_f32 v[118:119], v[152:153], v[118:119], v[156:157]
	v_mov_b32_dpp v116, v116 row_ror:1 row_mask:0xf bank_mask:0xf
	v_mov_b32_dpp v117, v117 row_ror:1 row_mask:0xf bank_mask:0xf
	v_mov_b32_dpp v123, v123 row_ror:15 row_mask:0xf bank_mask:0xf
	v_pk_fma_f32 v[112:113], v[148:149], v[112:113], v[118:119]
	v_pk_fma_f32 v[122:123], v[154:155], v[122:123], v[158:159]
	v_pk_fma_f32 v[192:193], v[144:145], v[116:117], v[112:113]
	v_add_u32_e32 v112, s10, v247
	v_readlane_b32 s10, v255, 1
	v_mov_b32_dpp v120, v120 row_ror:1 row_mask:0xf bank_mask:0xf
	v_mov_b32_dpp v121, v121 row_ror:1 row_mask:0xf bank_mask:0xf
	v_pk_fma_f32 v[114:115], v[150:151], v[114:115], v[122:123]
	v_add_u32_e32 v243, s10, v247
	v_pk_fma_f32 v[190:191], v[146:147], v[120:121], v[114:115]
	ds_read_b128 v[112:115], v112
	ds_read_b128 v[116:119], v243 offset:2048
	v_mov_b32_dpp v124, v124 row_ror:1 row_mask:0xf bank_mask:0xf
	v_mov_b32_dpp v125, v125 row_ror:1 row_mask:0xf bank_mask:0xf
	v_pk_fma_f32 v[194:195], v[146:147], v[124:125], v[126:127]
	s_waitcnt lgkmcnt(1)
	v_pk_mul_f32 v[114:115], v[174:175], v[114:115]
	s_waitcnt lgkmcnt(0)
	v_pk_mul_f32 v[220:221], v[178:179], v[118:119]
	v_pk_mul_f32 v[222:223], v[182:183], v[116:117]
	v_cndmask_b32_e32 v116, v100, v104, vcc
	v_cndmask_b32_e32 v117, v101, v105, vcc
	v_cndmask_b32_e32 v118, v102, v106, vcc
	v_cndmask_b32_e32 v119, v103, v107, vcc
	v_pk_mul_f32 v[112:113], v[180:181], v[112:113]
	v_mov_b32_dpp v116, v116 row_ror:15 row_mask:0xf bank_mask:0xf
	v_mov_b32_dpp v117, v117 row_ror:15 row_mask:0xf bank_mask:0xf
	v_mov_b32_dpp v118, v118 row_ror:15 row_mask:0xf bank_mask:0xf
	v_mov_b32_dpp v119, v119 row_ror:15 row_mask:0xf bank_mask:0xf
	v_cndmask_b32_e64 v112, v100, v112, s[6:7]
	v_cndmask_b32_e64 v113, v101, v113, s[6:7]
	v_cndmask_b32_e64 v114, v102, v114, s[6:7]
	v_cndmask_b32_e64 v115, v103, v115, s[6:7]
	v_pk_fma_f32 v[118:119], v[154:155], v[118:119], v[158:159]
	v_pk_fma_f32 v[116:117], v[152:153], v[116:117], v[156:157]
	v_mov_b32_dpp v112, v112 row_ror:1 row_mask:0xf bank_mask:0xf
	v_mov_b32_dpp v113, v113 row_ror:1 row_mask:0xf bank_mask:0xf
	v_mov_b32_dpp v114, v114 row_ror:1 row_mask:0xf bank_mask:0xf
	v_mov_b32_dpp v115, v115 row_ror:1 row_mask:0xf bank_mask:0xf
	v_pk_fma_f32 v[116:117], v[148:149], v[100:101], v[116:117]
	v_pk_fma_f32 v[118:119], v[150:151], v[102:103], v[118:119]
	v_pk_fma_f32 v[126:127], v[144:145], v[112:113], v[116:117]
	v_pk_fma_f32 v[124:125], v[146:147], v[114:115], v[118:119]
	v_cndmask_b32_e32 v112, v104, v96, vcc
	v_cndmask_b32_e32 v113, v105, v97, vcc
	v_cndmask_b32_e32 v114, v106, v98, vcc
	v_cndmask_b32_e32 v115, v107, v99, vcc
	v_mov_b32_dpp v112, v112 row_ror:15 row_mask:0xf bank_mask:0xf
	v_mov_b32_dpp v113, v113 row_ror:15 row_mask:0xf bank_mask:0xf
	v_mov_b32_dpp v114, v114 row_ror:15 row_mask:0xf bank_mask:0xf
	v_mov_b32_dpp v115, v115 row_ror:15 row_mask:0xf bank_mask:0xf
	v_cndmask_b32_e64 v100, v104, v100, s[6:7]
	v_cndmask_b32_e64 v101, v105, v101, s[6:7]
	v_cndmask_b32_e64 v102, v106, v102, s[6:7]
	v_cndmask_b32_e64 v103, v107, v103, s[6:7]
	v_pk_fma_f32 v[114:115], v[154:155], v[114:115], v[158:159]
	v_pk_fma_f32 v[112:113], v[152:153], v[112:113], v[156:157]
	v_mov_b32_dpp v100, v100 row_ror:1 row_mask:0xf bank_mask:0xf
	v_mov_b32_dpp v101, v101 row_ror:1 row_mask:0xf bank_mask:0xf
	v_mov_b32_dpp v102, v102 row_ror:1 row_mask:0xf bank_mask:0xf
	v_mov_b32_dpp v103, v103 row_ror:1 row_mask:0xf bank_mask:0xf
	v_pk_fma_f32 v[112:113], v[148:149], v[104:105], v[112:113]
	v_pk_fma_f32 v[114:115], v[150:151], v[106:107], v[114:115]
	v_pk_fma_f32 v[122:123], v[144:145], v[100:101], v[112:113]
	v_pk_fma_f32 v[120:121], v[146:147], v[102:103], v[114:115]
	v_cndmask_b32_e32 v101, v96, v88, vcc
	v_cndmask_b32_e32 v103, v97, v89, vcc
	v_add_co_u32_e64 v212, s[10:11], s23, v212
	v_mov_b32_dpp v102, v101 row_ror:15 row_mask:0xf bank_mask:0xf
	v_mov_b32_dpp v103, v103 row_ror:15 row_mask:0xf bank_mask:0xf
	v_cndmask_b32_e64 v100, v96, v104, s[6:7]
	v_cndmask_b32_e64 v101, v97, v105, s[6:7]
	v_pk_fma_f32 v[102:103], v[152:153], v[102:103], v[156:157]
	v_addc_co_u32_e64 v213, s[10:11], 0, v213, s[10:11]
	v_mov_b32_dpp v100, v100 row_ror:1 row_mask:0xf bank_mask:0xf
	v_mov_b32_dpp v101, v101 row_ror:1 row_mask:0xf bank_mask:0xf
	v_cndmask_b32_e32 v105, v98, v90, vcc
	v_pk_fma_f32 v[102:103], v[148:149], v[96:97], v[102:103]
	v_add_co_u32_e64 v210, s[10:11], s23, v210
	v_cndmask_b32_e64 v104, v98, v106, s[6:7]
	v_mov_b32_dpp v106, v105 row_ror:15 row_mask:0xf bank_mask:0xf
	v_cndmask_b32_e64 v105, v99, v107, s[6:7]
	v_cndmask_b32_e32 v107, v99, v91, vcc
	v_pk_fma_f32 v[118:119], v[144:145], v[100:101], v[102:103]
	v_cndmask_b32_e32 v100, v88, v222, vcc
	v_cndmask_b32_e32 v101, v89, v223, vcc
	v_addc_co_u32_e64 v211, s[10:11], 0, v211, s[10:11]
	v_mov_b32_dpp v107, v107 row_ror:15 row_mask:0xf bank_mask:0xf
	v_mov_b32_dpp v100, v100 row_ror:15 row_mask:0xf bank_mask:0xf
	v_mov_b32_dpp v101, v101 row_ror:15 row_mask:0xf bank_mask:0xf
	v_cndmask_b32_e32 v102, v90, v220, vcc
	v_cndmask_b32_e32 v103, v91, v221, vcc
	v_add_co_u32_e64 v208, s[10:11], s23, v208
	v_pk_fma_f32 v[106:107], v[154:155], v[106:107], v[158:159]
	v_cndmask_b32_e64 v96, v88, v96, s[6:7]
	v_cndmask_b32_e64 v97, v89, v97, s[6:7]
	v_mov_b32_dpp v102, v102 row_ror:15 row_mask:0xf bank_mask:0xf
	v_mov_b32_dpp v103, v103 row_ror:15 row_mask:0xf bank_mask:0xf
	v_pk_fma_f32 v[100:101], v[152:153], v[100:101], v[156:157]
	v_addc_co_u32_e64 v209, s[10:11], 0, v209, s[10:11]
	v_pk_fma_f32 v[106:107], v[150:151], v[98:99], v[106:107]
	v_mov_b32_dpp v96, v96 row_ror:1 row_mask:0xf bank_mask:0xf
	v_mov_b32_dpp v97, v97 row_ror:1 row_mask:0xf bank_mask:0xf
	v_cndmask_b32_e64 v98, v90, v98, s[6:7]
	v_cndmask_b32_e64 v99, v91, v99, s[6:7]
	v_pk_fma_f32 v[102:103], v[154:155], v[102:103], v[158:159]
	v_pk_fma_f32 v[88:89], v[148:149], v[88:89], v[100:101]
	v_add_co_u32_e64 v206, s[10:11], s23, v206
	v_mov_b32_dpp v104, v104 row_ror:1 row_mask:0xf bank_mask:0xf
	v_mov_b32_dpp v105, v105 row_ror:1 row_mask:0xf bank_mask:0xf
	v_mov_b32_dpp v98, v98 row_ror:1 row_mask:0xf bank_mask:0xf
	v_mov_b32_dpp v99, v99 row_ror:1 row_mask:0xf bank_mask:0xf
	v_pk_fma_f32 v[90:91], v[150:151], v[90:91], v[102:103]
	v_pk_fma_f32 v[114:115], v[144:145], v[96:97], v[88:89]
	v_addc_co_u32_e64 v207, s[10:11], 0, v207, s[10:11]
	v_add_u32_e32 v144, 0xfffffc10, v246
	v_pk_fma_f32 v[116:117], v[146:147], v[104:105], v[106:107]
	v_pk_fma_f32 v[112:113], v[146:147], v[98:99], v[90:91]
	global_load_dwordx4 v[88:91], v[212:213], off offset:2048
	global_load_dwordx4 v[96:99], v[210:211], off offset:2048
	global_load_dwordx4 v[100:103], v[208:209], off offset:2048
	global_load_dwordx4 v[104:107], v[206:207], off offset:2048
	s_waitcnt vmcnt(4)
	ds_read_b128 v[144:147], v144
	ds_read_b128 v[148:151], v244 offset:2064
	v_readlane_b32 s10, v255, 2
	s_waitcnt lgkmcnt(1)
	v_pk_mul_f32 v[144:145], v[170:171], v[144:145]
	s_waitcnt lgkmcnt(0)
	v_pk_mul_f32 v[154:155], v[172:173], v[148:149]
	v_cndmask_b32_e32 v148, v84, v108, vcc
	v_cndmask_b32_e32 v149, v85, v109, vcc
	v_pk_mul_f32 v[152:153], v[168:169], v[150:151]
	v_mov_b32_dpp v148, v148 row_ror:15 row_mask:0xf bank_mask:0xf
	v_mov_b32_dpp v149, v149 row_ror:15 row_mask:0xf bank_mask:0xf
	v_cndmask_b32_e32 v150, v86, v110, vcc
	v_cndmask_b32_e32 v151, v87, v111, vcc
	v_pk_mul_f32 v[146:147], v[166:167], v[146:147]
	v_cndmask_b32_e64 v144, v84, v144, s[6:7]
	v_cndmask_b32_e64 v145, v85, v145, s[6:7]
	v_mov_b32_dpp v150, v150 row_ror:15 row_mask:0xf bank_mask:0xf
	v_mov_b32_dpp v151, v151 row_ror:15 row_mask:0xf bank_mask:0xf
	v_pk_fma_f32 v[148:149], v[136:137], v[148:149], v[140:141]
	v_mov_b32_dpp v144, v144 row_ror:1 row_mask:0xf bank_mask:0xf
	v_mov_b32_dpp v145, v145 row_ror:1 row_mask:0xf bank_mask:0xf
	v_cndmask_b32_e64 v146, v86, v146, s[6:7]
	v_cndmask_b32_e64 v147, v87, v147, s[6:7]
	v_pk_fma_f32 v[150:151], v[138:139], v[150:151], v[142:143]
	v_pk_fma_f32 v[148:149], v[132:133], v[84:85], v[148:149]
	v_mov_b32_dpp v146, v146 row_ror:1 row_mask:0xf bank_mask:0xf
	v_mov_b32_dpp v147, v147 row_ror:1 row_mask:0xf bank_mask:0xf
	v_pk_fma_f32 v[150:151], v[134:135], v[86:87], v[150:151]
	v_pk_fma_f32 v[158:159], v[128:129], v[144:145], v[148:149]
	v_cndmask_b32_e32 v144, v108, v92, vcc
	v_cndmask_b32_e32 v145, v109, v93, vcc
	v_pk_fma_f32 v[156:157], v[130:131], v[146:147], v[150:151]
	v_mov_b32_dpp v144, v144 row_ror:15 row_mask:0xf bank_mask:0xf
	v_mov_b32_dpp v145, v145 row_ror:15 row_mask:0xf bank_mask:0xf
	v_cndmask_b32_e32 v146, v110, v94, vcc
	v_cndmask_b32_e32 v147, v111, v95, vcc
	v_cndmask_b32_e64 v84, v108, v84, s[6:7]
	v_cndmask_b32_e64 v85, v109, v85, s[6:7]
	v_mov_b32_dpp v146, v146 row_ror:15 row_mask:0xf bank_mask:0xf
	v_mov_b32_dpp v147, v147 row_ror:15 row_mask:0xf bank_mask:0xf
	v_pk_fma_f32 v[144:145], v[136:137], v[144:145], v[140:141]
	v_mov_b32_dpp v84, v84 row_ror:1 row_mask:0xf bank_mask:0xf
	v_mov_b32_dpp v85, v85 row_ror:1 row_mask:0xf bank_mask:0xf
	v_cndmask_b32_e64 v86, v110, v86, s[6:7]
	v_cndmask_b32_e64 v87, v111, v87, s[6:7]
	v_pk_fma_f32 v[146:147], v[138:139], v[146:147], v[142:143]
	v_pk_fma_f32 v[144:145], v[132:133], v[108:109], v[144:145]
	v_mov_b32_dpp v86, v86 row_ror:1 row_mask:0xf bank_mask:0xf
	v_mov_b32_dpp v87, v87 row_ror:1 row_mask:0xf bank_mask:0xf
	v_pk_fma_f32 v[146:147], v[134:135], v[110:111], v[146:147]
	v_pk_fma_f32 v[150:151], v[128:129], v[84:85], v[144:145]
	v_cndmask_b32_e32 v85, v92, v80, vcc
	v_pk_fma_f32 v[148:149], v[130:131], v[86:87], v[146:147]
	v_cndmask_b32_e64 v84, v92, v108, s[6:7]
	v_mov_b32_dpp v86, v85 row_ror:15 row_mask:0xf bank_mask:0xf
	v_cndmask_b32_e64 v85, v93, v109, s[6:7]
	v_cndmask_b32_e32 v109, v94, v82, vcc
	v_cndmask_b32_e32 v87, v93, v81, vcc
	v_cndmask_b32_e64 v108, v94, v110, s[6:7]
	v_mov_b32_dpp v110, v109 row_ror:15 row_mask:0xf bank_mask:0xf
	v_cndmask_b32_e64 v109, v95, v111, s[6:7]
	v_cndmask_b32_e32 v111, v95, v83, vcc
	v_mov_b32_dpp v87, v87 row_ror:15 row_mask:0xf bank_mask:0xf
	v_pk_fma_f32 v[86:87], v[136:137], v[86:87], v[140:141]
	v_mov_b32_dpp v111, v111 row_ror:15 row_mask:0xf bank_mask:0xf
	v_pk_fma_f32 v[110:111], v[138:139], v[110:111], v[142:143]
	v_mov_b32_dpp v84, v84 row_ror:1 row_mask:0xf bank_mask:0xf
	v_mov_b32_dpp v85, v85 row_ror:1 row_mask:0xf bank_mask:0xf
	v_mov_b32_dpp v108, v108 row_ror:1 row_mask:0xf bank_mask:0xf
	v_mov_b32_dpp v109, v109 row_ror:1 row_mask:0xf bank_mask:0xf
	v_pk_fma_f32 v[110:111], v[134:135], v[94:95], v[110:111]
	v_pk_fma_f32 v[86:87], v[132:133], v[92:93], v[86:87]
	v_pk_fma_f32 v[108:109], v[130:131], v[108:109], v[110:111]
	v_pk_fma_f32 v[110:111], v[128:129], v[84:85], v[86:87]
	v_cndmask_b32_e32 v85, v80, v154, vcc
	v_cndmask_b32_e32 v87, v81, v155, vcc
	v_cndmask_b32_e64 v84, v80, v92, s[6:7]
	v_mov_b32_dpp v86, v85 row_ror:15 row_mask:0xf bank_mask:0xf
	v_cndmask_b32_e64 v85, v81, v93, s[6:7]
	v_cndmask_b32_e32 v93, v82, v152, vcc
	v_mov_b32_dpp v87, v87 row_ror:15 row_mask:0xf bank_mask:0xf
	v_cndmask_b32_e64 v92, v82, v94, s[6:7]
	v_mov_b32_dpp v94, v93 row_ror:15 row_mask:0xf bank_mask:0xf
	v_cndmask_b32_e64 v93, v83, v95, s[6:7]
	v_cndmask_b32_e32 v95, v83, v153, vcc
	v_pk_fma_f32 v[86:87], v[136:137], v[86:87], v[140:141]
	v_mov_b32_dpp v84, v84 row_ror:1 row_mask:0xf bank_mask:0xf
	v_mov_b32_dpp v95, v95 row_ror:15 row_mask:0xf bank_mask:0xf
	v_mov_b32_dpp v85, v85 row_ror:1 row_mask:0xf bank_mask:0xf
	v_pk_fma_f32 v[94:95], v[138:139], v[94:95], v[142:143]
	v_pk_fma_f32 v[80:81], v[132:133], v[80:81], v[86:87]
	v_mov_b32_dpp v92, v92 row_ror:1 row_mask:0xf bank_mask:0xf
	v_mov_b32_dpp v93, v93 row_ror:1 row_mask:0xf bank_mask:0xf
	v_pk_fma_f32 v[82:83], v[134:135], v[82:83], v[94:95]
	v_pk_fma_f32 v[94:95], v[128:129], v[84:85], v[80:81]
	v_add_u32_e32 v80, 0xfffffc10, v245
	v_pk_fma_f32 v[92:93], v[130:131], v[92:93], v[82:83]
	ds_read_b128 v[80:83], v80
	ds_read_b128 v[84:87], v243 offset:2064
	s_waitcnt lgkmcnt(1)
	v_pk_mul_f32 v[82:83], v[174:175], v[82:83]
	s_waitcnt lgkmcnt(0)
	v_pk_mul_f32 v[220:221], v[178:179], v[86:87]
	v_pk_mul_f32 v[222:223], v[182:183], v[84:85]
	v_cndmask_b32_e32 v84, v72, v76, vcc
	v_cndmask_b32_e32 v85, v73, v77, vcc
	v_cndmask_b32_e32 v86, v74, v78, vcc
	v_cndmask_b32_e32 v87, v75, v79, vcc
	v_pk_mul_f32 v[80:81], v[180:181], v[80:81]
	v_mov_b32_dpp v84, v84 row_ror:15 row_mask:0xf bank_mask:0xf
	v_mov_b32_dpp v85, v85 row_ror:15 row_mask:0xf bank_mask:0xf
	v_mov_b32_dpp v86, v86 row_ror:15 row_mask:0xf bank_mask:0xf
	v_mov_b32_dpp v87, v87 row_ror:15 row_mask:0xf bank_mask:0xf
	v_cndmask_b32_e64 v80, v72, v80, s[6:7]
	v_cndmask_b32_e64 v81, v73, v81, s[6:7]
	v_cndmask_b32_e64 v82, v74, v82, s[6:7]
	v_cndmask_b32_e64 v83, v75, v83, s[6:7]
	v_pk_fma_f32 v[84:85], v[136:137], v[84:85], v[140:141]
	v_pk_fma_f32 v[86:87], v[138:139], v[86:87], v[142:143]
	v_mov_b32_dpp v80, v80 row_ror:1 row_mask:0xf bank_mask:0xf
	v_mov_b32_dpp v81, v81 row_ror:1 row_mask:0xf bank_mask:0xf
	v_mov_b32_dpp v82, v82 row_ror:1 row_mask:0xf bank_mask:0xf
	v_mov_b32_dpp v83, v83 row_ror:1 row_mask:0xf bank_mask:0xf
	v_pk_fma_f32 v[86:87], v[134:135], v[74:75], v[86:87]
	v_pk_fma_f32 v[84:85], v[132:133], v[72:73], v[84:85]
	v_pk_fma_f32 v[152:153], v[130:131], v[82:83], v[86:87]
	v_pk_fma_f32 v[154:155], v[128:129], v[80:81], v[84:85]
	v_cndmask_b32_e32 v80, v76, v68, vcc
	v_cndmask_b32_e32 v81, v77, v69, vcc
	v_cndmask_b32_e32 v82, v78, v70, vcc
	v_cndmask_b32_e32 v83, v79, v71, vcc
	v_mov_b32_dpp v80, v80 row_ror:15 row_mask:0xf bank_mask:0xf
	v_mov_b32_dpp v81, v81 row_ror:15 row_mask:0xf bank_mask:0xf
	v_mov_b32_dpp v82, v82 row_ror:15 row_mask:0xf bank_mask:0xf
	v_mov_b32_dpp v83, v83 row_ror:15 row_mask:0xf bank_mask:0xf
	v_cndmask_b32_e64 v72, v76, v72, s[6:7]
	v_cndmask_b32_e64 v73, v77, v73, s[6:7]
	v_cndmask_b32_e64 v74, v78, v74, s[6:7]
	v_cndmask_b32_e64 v75, v79, v75, s[6:7]
	v_pk_fma_f32 v[80:81], v[136:137], v[80:81], v[140:141]
	v_pk_fma_f32 v[82:83], v[138:139], v[82:83], v[142:143]
	v_mov_b32_dpp v72, v72 row_ror:1 row_mask:0xf bank_mask:0xf
	v_mov_b32_dpp v73, v73 row_ror:1 row_mask:0xf bank_mask:0xf
	v_mov_b32_dpp v74, v74 row_ror:1 row_mask:0xf bank_mask:0xf
	v_mov_b32_dpp v75, v75 row_ror:1 row_mask:0xf bank_mask:0xf
	v_pk_fma_f32 v[82:83], v[134:135], v[78:79], v[82:83]
	v_pk_fma_f32 v[80:81], v[132:133], v[76:77], v[80:81]
	v_pk_fma_f32 v[144:145], v[130:131], v[74:75], v[82:83]
	v_pk_fma_f32 v[146:147], v[128:129], v[72:73], v[80:81]
	v_cndmask_b32_e32 v73, v68, v64, vcc
	v_cndmask_b32_e32 v75, v69, v65, vcc
	v_cndmask_b32_e64 v72, v68, v76, s[6:7]
	v_mov_b32_dpp v74, v73 row_ror:15 row_mask:0xf bank_mask:0xf
	v_mov_b32_dpp v75, v75 row_ror:15 row_mask:0xf bank_mask:0xf
	v_cndmask_b32_e64 v73, v69, v77, s[6:7]
	v_cndmask_b32_e32 v77, v70, v66, vcc
	v_pk_fma_f32 v[74:75], v[136:137], v[74:75], v[140:141]
	v_mov_b32_dpp v72, v72 row_ror:1 row_mask:0xf bank_mask:0xf
	v_mov_b32_dpp v73, v73 row_ror:1 row_mask:0xf bank_mask:0xf
	v_cndmask_b32_e64 v76, v70, v78, s[6:7]
	v_mov_b32_dpp v78, v77 row_ror:15 row_mask:0xf bank_mask:0xf
	v_cndmask_b32_e64 v77, v71, v79, s[6:7]
	v_cndmask_b32_e32 v79, v71, v67, vcc
	v_pk_fma_f32 v[74:75], v[132:133], v[68:69], v[74:75]
	v_cndmask_b32_e64 v68, v64, v68, s[6:7]
	v_mov_b32_dpp v79, v79 row_ror:15 row_mask:0xf bank_mask:0xf
	v_pk_fma_f32 v[86:87], v[128:129], v[72:73], v[74:75]
	v_cndmask_b32_e32 v72, v64, v222, vcc
	v_cndmask_b32_e32 v73, v65, v223, vcc
	v_cndmask_b32_e32 v74, v66, v220, vcc
	v_cndmask_b32_e32 v75, v67, v221, vcc
	v_pk_fma_f32 v[78:79], v[138:139], v[78:79], v[142:143]
	v_mov_b32_dpp v72, v72 row_ror:15 row_mask:0xf bank_mask:0xf
	v_mov_b32_dpp v73, v73 row_ror:15 row_mask:0xf bank_mask:0xf
	v_mov_b32_dpp v74, v74 row_ror:15 row_mask:0xf bank_mask:0xf
	v_mov_b32_dpp v75, v75 row_ror:15 row_mask:0xf bank_mask:0xf
	v_pk_fma_f32 v[78:79], v[134:135], v[70:71], v[78:79]
	v_cndmask_b32_e64 v69, v65, v69, s[6:7]
	v_cndmask_b32_e64 v70, v66, v70, s[6:7]
	v_cndmask_b32_e64 v71, v67, v71, s[6:7]
	v_pk_fma_f32 v[74:75], v[138:139], v[74:75], v[142:143]
	v_pk_fma_f32 v[72:73], v[136:137], v[72:73], v[140:141]
	v_mov_b32_dpp v76, v76 row_ror:1 row_mask:0xf bank_mask:0xf
	v_mov_b32_dpp v77, v77 row_ror:1 row_mask:0xf bank_mask:0xf
	v_mov_b32_dpp v68, v68 row_ror:1 row_mask:0xf bank_mask:0xf
	v_mov_b32_dpp v69, v69 row_ror:1 row_mask:0xf bank_mask:0xf
	v_mov_b32_dpp v70, v70 row_ror:1 row_mask:0xf bank_mask:0xf
	v_mov_b32_dpp v71, v71 row_ror:1 row_mask:0xf bank_mask:0xf
	v_pk_fma_f32 v[66:67], v[134:135], v[66:67], v[74:75]
	v_pk_fma_f32 v[64:65], v[132:133], v[64:65], v[72:73]
	v_pk_fma_f32 v[84:85], v[130:131], v[76:77], v[78:79]
	v_pk_fma_f32 v[80:81], v[130:131], v[70:71], v[66:67]
	v_pk_fma_f32 v[82:83], v[128:129], v[68:69], v[64:65]
	global_load_dwordx4 v[64:67], v[212:213], off offset:2064
	global_load_dwordx4 v[68:71], v[210:211], off offset:2064
	global_load_dwordx4 v[72:75], v[208:209], off offset:2064
	global_load_dwordx4 v[76:79], v[206:207], off offset:2064
	v_add_u32_e32 v128, s10, v247
	ds_read_b128 v[128:131], v128
	ds_read_b128 v[132:135], v244 offset:2560
	s_movk_i32 s10, 0x2c00
	s_waitcnt lgkmcnt(1)
	v_pk_mul_f32 v[128:129], v[170:171], v[128:129]
	s_waitcnt lgkmcnt(0)
	v_pk_mul_f32 v[138:139], v[172:173], v[132:133]
	v_cndmask_b32_e32 v132, v52, v60, vcc
	v_cndmask_b32_e32 v133, v53, v61, vcc
	v_pk_mul_f32 v[136:137], v[168:169], v[134:135]
	v_mov_b32_dpp v132, v132 row_ror:15 row_mask:0xf bank_mask:0xf
	v_mov_b32_dpp v133, v133 row_ror:15 row_mask:0xf bank_mask:0xf
	v_cndmask_b32_e32 v134, v54, v62, vcc
	v_cndmask_b32_e32 v135, v55, v63, vcc
	v_pk_mul_f32 v[130:131], v[166:167], v[130:131]
	v_cndmask_b32_e64 v128, v52, v128, s[6:7]
	v_cndmask_b32_e64 v129, v53, v129, s[6:7]
	v_mov_b32_dpp v134, v134 row_ror:15 row_mask:0xf bank_mask:0xf
	v_mov_b32_dpp v135, v135 row_ror:15 row_mask:0xf bank_mask:0xf
	s_waitcnt vmcnt(4)
	v_pk_fma_f32 v[132:133], v[100:101], v[132:133], v[104:105]
	v_mov_b32_dpp v128, v128 row_ror:1 row_mask:0xf bank_mask:0xf
	v_mov_b32_dpp v129, v129 row_ror:1 row_mask:0xf bank_mask:0xf
	v_cndmask_b32_e64 v130, v54, v130, s[6:7]
	v_cndmask_b32_e64 v131, v55, v131, s[6:7]
	v_pk_fma_f32 v[134:135], v[102:103], v[134:135], v[106:107]
	v_pk_fma_f32 v[140:141], v[96:97], v[52:53], v[132:133]
	v_mov_b32_dpp v130, v130 row_ror:1 row_mask:0xf bank_mask:0xf
	v_mov_b32_dpp v131, v131 row_ror:1 row_mask:0xf bank_mask:0xf
	v_pk_fma_f32 v[132:133], v[98:99], v[54:55], v[134:135]
	v_pk_fma_f32 v[134:135], v[88:89], v[128:129], v[140:141]
	v_cndmask_b32_e32 v128, v60, v56, vcc
	v_cndmask_b32_e32 v129, v61, v57, vcc
	v_pk_fma_f32 v[132:133], v[90:91], v[130:131], v[132:133]
	v_mov_b32_dpp v128, v128 row_ror:15 row_mask:0xf bank_mask:0xf
	v_mov_b32_dpp v129, v129 row_ror:15 row_mask:0xf bank_mask:0xf
	v_cndmask_b32_e32 v130, v62, v58, vcc
	v_cndmask_b32_e32 v131, v63, v59, vcc
	v_cndmask_b32_e64 v52, v60, v52, s[6:7]
	v_cndmask_b32_e64 v53, v61, v53, s[6:7]
	v_mov_b32_dpp v130, v130 row_ror:15 row_mask:0xf bank_mask:0xf
	v_mov_b32_dpp v131, v131 row_ror:15 row_mask:0xf bank_mask:0xf
	v_pk_fma_f32 v[128:129], v[100:101], v[128:129], v[104:105]
	v_mov_b32_dpp v52, v52 row_ror:1 row_mask:0xf bank_mask:0xf
	v_mov_b32_dpp v53, v53 row_ror:1 row_mask:0xf bank_mask:0xf
	v_cndmask_b32_e64 v54, v62, v54, s[6:7]
	v_cndmask_b32_e64 v55, v63, v55, s[6:7]
	v_pk_fma_f32 v[130:131], v[102:103], v[130:131], v[106:107]
	v_pk_fma_f32 v[140:141], v[96:97], v[60:61], v[128:129]
	v_mov_b32_dpp v54, v54 row_ror:1 row_mask:0xf bank_mask:0xf
	v_mov_b32_dpp v55, v55 row_ror:1 row_mask:0xf bank_mask:0xf
	v_pk_fma_f32 v[128:129], v[98:99], v[62:63], v[130:131]
	v_pk_fma_f32 v[130:131], v[88:89], v[52:53], v[140:141]
	v_cndmask_b32_e32 v53, v56, v48, vcc
	v_pk_fma_f32 v[128:129], v[90:91], v[54:55], v[128:129]
	v_cndmask_b32_e64 v52, v56, v60, s[6:7]
	v_mov_b32_dpp v54, v53 row_ror:15 row_mask:0xf bank_mask:0xf
	v_cndmask_b32_e64 v53, v57, v61, s[6:7]
	v_cndmask_b32_e32 v61, v58, v50, vcc
	v_cndmask_b32_e32 v55, v57, v49, vcc
	v_cndmask_b32_e64 v60, v58, v62, s[6:7]
	v_mov_b32_dpp v62, v61 row_ror:15 row_mask:0xf bank_mask:0xf
	v_cndmask_b32_e64 v61, v59, v63, s[6:7]
	v_cndmask_b32_e32 v63, v59, v51, vcc
	v_mov_b32_dpp v55, v55 row_ror:15 row_mask:0xf bank_mask:0xf
	v_pk_fma_f32 v[54:55], v[100:101], v[54:55], v[104:105]
	v_mov_b32_dpp v63, v63 row_ror:15 row_mask:0xf bank_mask:0xf
	v_pk_fma_f32 v[62:63], v[102:103], v[62:63], v[106:107]
	v_mov_b32_dpp v52, v52 row_ror:1 row_mask:0xf bank_mask:0xf
	v_mov_b32_dpp v53, v53 row_ror:1 row_mask:0xf bank_mask:0xf
	v_mov_b32_dpp v60, v60 row_ror:1 row_mask:0xf bank_mask:0xf
	v_mov_b32_dpp v61, v61 row_ror:1 row_mask:0xf bank_mask:0xf
	v_pk_fma_f32 v[54:55], v[96:97], v[56:57], v[54:55]
	v_pk_fma_f32 v[62:63], v[98:99], v[58:59], v[62:63]
	s_nop 0
	v_pk_fma_f32 v[60:61], v[90:91], v[60:61], v[62:63]
	v_pk_fma_f32 v[62:63], v[88:89], v[52:53], v[54:55]
	v_cndmask_b32_e32 v53, v48, v138, vcc
	v_cndmask_b32_e32 v55, v49, v139, vcc
	v_cndmask_b32_e64 v52, v48, v56, s[6:7]
	v_mov_b32_dpp v54, v53 row_ror:15 row_mask:0xf bank_mask:0xf
	v_cndmask_b32_e64 v53, v49, v57, s[6:7]
	v_cndmask_b32_e32 v57, v50, v136, vcc
	v_mov_b32_dpp v55, v55 row_ror:15 row_mask:0xf bank_mask:0xf
	v_cndmask_b32_e64 v56, v50, v58, s[6:7]
	v_mov_b32_dpp v58, v57 row_ror:15 row_mask:0xf bank_mask:0xf
	v_cndmask_b32_e64 v57, v51, v59, s[6:7]
	v_cndmask_b32_e32 v59, v51, v137, vcc
	v_pk_fma_f32 v[54:55], v[100:101], v[54:55], v[104:105]
	v_mov_b32_dpp v52, v52 row_ror:1 row_mask:0xf bank_mask:0xf
	v_mov_b32_dpp v59, v59 row_ror:15 row_mask:0xf bank_mask:0xf
	v_mov_b32_dpp v53, v53 row_ror:1 row_mask:0xf bank_mask:0xf
	v_pk_fma_f32 v[58:59], v[102:103], v[58:59], v[106:107]
	v_pk_fma_f32 v[48:49], v[96:97], v[48:49], v[54:55]
	v_mov_b32_dpp v56, v56 row_ror:1 row_mask:0xf bank_mask:0xf
	v_mov_b32_dpp v57, v57 row_ror:1 row_mask:0xf bank_mask:0xf
	v_pk_fma_f32 v[50:51], v[98:99], v[50:51], v[58:59]
	v_pk_fma_f32 v[58:59], v[88:89], v[52:53], v[48:49]
	v_add_u32_e32 v48, s95, v247
	v_pk_fma_f32 v[56:57], v[90:91], v[56:57], v[50:51]
	ds_read_b128 v[48:51], v48
	ds_read_b128 v[52:55], v243 offset:2560
	v_cndmask_b32_e32 v138, v46, v42, vcc
	v_cndmask_b32_e32 v139, v47, v43, vcc
	s_waitcnt lgkmcnt(1)
	v_pk_mul_f32 v[48:49], v[180:181], v[48:49]
	v_pk_mul_f32 v[50:51], v[174:175], v[50:51]
	v_cndmask_b32_e64 v48, v44, v48, s[6:7]
	v_cndmask_b32_e64 v49, v45, v49, s[6:7]
	v_mov_b32_dpp v138, v138 row_ror:15 row_mask:0xf bank_mask:0xf
	v_mov_b32_dpp v136, v48 row_ror:1 row_mask:0xf bank_mask:0xf
	v_cndmask_b32_e32 v48, v44, v40, vcc
	v_mov_b32_dpp v137, v49 row_ror:1 row_mask:0xf bank_mask:0xf
	v_cndmask_b32_e32 v49, v45, v41, vcc
	v_mov_b32_dpp v48, v48 row_ror:15 row_mask:0xf bank_mask:0xf
	v_mov_b32_dpp v139, v139 row_ror:15 row_mask:0xf bank_mask:0xf
	v_mov_b32_dpp v49, v49 row_ror:15 row_mask:0xf bank_mask:0xf
	v_cndmask_b32_e64 v50, v46, v50, s[6:7]
	v_cndmask_b32_e64 v51, v47, v51, s[6:7]
	v_pk_fma_f32 v[138:139], v[102:103], v[138:139], v[106:107]
	v_pk_fma_f32 v[48:49], v[100:101], v[48:49], v[104:105]
	v_mov_b32_dpp v50, v50 row_ror:1 row_mask:0xf bank_mask:0xf
	v_mov_b32_dpp v51, v51 row_ror:1 row_mask:0xf bank_mask:0xf
	v_pk_fma_f32 v[140:141], v[96:97], v[44:45], v[48:49]
	v_pk_fma_f32 v[48:49], v[98:99], v[46:47], v[138:139]
	v_cndmask_b32_e64 v44, v40, v44, s[6:7]
	v_cndmask_b32_e64 v45, v41, v45, s[6:7]
	v_pk_fma_f32 v[48:49], v[90:91], v[50:51], v[48:49]
	v_pk_fma_f32 v[50:51], v[88:89], v[136:137], v[140:141]
	v_mov_b32_dpp v136, v44 row_ror:1 row_mask:0xf bank_mask:0xf
	v_cndmask_b32_e32 v44, v40, v36, vcc
	v_mov_b32_dpp v137, v45 row_ror:1 row_mask:0xf bank_mask:0xf
	v_cndmask_b32_e32 v45, v41, v37, vcc
	v_cndmask_b32_e32 v138, v42, v38, vcc
	v_cndmask_b32_e32 v139, v43, v39, vcc
	v_mov_b32_dpp v44, v44 row_ror:15 row_mask:0xf bank_mask:0xf
	v_mov_b32_dpp v45, v45 row_ror:15 row_mask:0xf bank_mask:0xf
	v_mov_b32_dpp v138, v138 row_ror:15 row_mask:0xf bank_mask:0xf
	v_mov_b32_dpp v139, v139 row_ror:15 row_mask:0xf bank_mask:0xf
	v_cndmask_b32_e64 v46, v42, v46, s[6:7]
	v_cndmask_b32_e64 v47, v43, v47, s[6:7]
	v_pk_fma_f32 v[138:139], v[102:103], v[138:139], v[106:107]
	v_pk_fma_f32 v[44:45], v[100:101], v[44:45], v[104:105]
	v_mov_b32_dpp v46, v46 row_ror:1 row_mask:0xf bank_mask:0xf
	v_mov_b32_dpp v47, v47 row_ror:1 row_mask:0xf bank_mask:0xf
	v_pk_fma_f32 v[140:141], v[96:97], v[40:41], v[44:45]
	v_pk_fma_f32 v[44:45], v[98:99], v[42:43], v[138:139]
	v_cndmask_b32_e64 v40, v36, v40, s[6:7]
	v_cndmask_b32_e64 v41, v37, v41, s[6:7]
	s_waitcnt lgkmcnt(0)
	v_pk_mul_f32 v[54:55], v[178:179], v[54:55]
	v_pk_mul_f32 v[52:53], v[182:183], v[52:53]
	v_pk_fma_f32 v[44:45], v[90:91], v[46:47], v[44:45]
	v_pk_fma_f32 v[46:47], v[88:89], v[136:137], v[140:141]
	v_mov_b32_dpp v136, v40 row_ror:1 row_mask:0xf bank_mask:0xf
	v_cndmask_b32_e32 v40, v36, v32, vcc
	v_mov_b32_dpp v137, v41 row_ror:1 row_mask:0xf bank_mask:0xf
	v_cndmask_b32_e32 v41, v37, v33, vcc
	v_cndmask_b32_e32 v138, v38, v34, vcc
	v_cndmask_b32_e32 v139, v39, v35, vcc
	v_mov_b32_dpp v40, v40 row_ror:15 row_mask:0xf bank_mask:0xf
	v_mov_b32_dpp v41, v41 row_ror:15 row_mask:0xf bank_mask:0xf
	v_mov_b32_dpp v138, v138 row_ror:15 row_mask:0xf bank_mask:0xf
	v_mov_b32_dpp v139, v139 row_ror:15 row_mask:0xf bank_mask:0xf
	v_cndmask_b32_e32 v52, v32, v52, vcc
	v_cndmask_b32_e32 v53, v33, v53, vcc
	v_cndmask_b32_e32 v54, v34, v54, vcc
	v_cndmask_b32_e32 v55, v35, v55, vcc
	v_pk_fma_f32 v[138:139], v[102:103], v[138:139], v[106:107]
	v_pk_fma_f32 v[40:41], v[100:101], v[40:41], v[104:105]
	v_mov_b32_dpp v52, v52 row_ror:15 row_mask:0xf bank_mask:0xf
	v_mov_b32_dpp v53, v53 row_ror:15 row_mask:0xf bank_mask:0xf
	v_mov_b32_dpp v54, v54 row_ror:15 row_mask:0xf bank_mask:0xf
	v_mov_b32_dpp v55, v55 row_ror:15 row_mask:0xf bank_mask:0xf
	v_cndmask_b32_e64 v42, v38, v42, s[6:7]
	v_cndmask_b32_e64 v43, v39, v43, s[6:7]
	v_pk_fma_f32 v[140:141], v[96:97], v[36:37], v[40:41]
	v_pk_fma_f32 v[40:41], v[98:99], v[38:39], v[138:139]
	v_cndmask_b32_e64 v36, v32, v36, s[6:7]
	v_cndmask_b32_e64 v37, v33, v37, s[6:7]
	v_cndmask_b32_e64 v38, v34, v38, s[6:7]
	v_cndmask_b32_e64 v39, v35, v39, s[6:7]
	v_pk_fma_f32 v[54:55], v[102:103], v[54:55], v[106:107]
	v_pk_fma_f32 v[52:53], v[100:101], v[52:53], v[104:105]
	v_mov_b32_dpp v36, v36 row_ror:1 row_mask:0xf bank_mask:0xf
	v_mov_b32_dpp v37, v37 row_ror:1 row_mask:0xf bank_mask:0xf
	v_mov_b32_dpp v38, v38 row_ror:1 row_mask:0xf bank_mask:0xf
	v_mov_b32_dpp v39, v39 row_ror:1 row_mask:0xf bank_mask:0xf
	v_pk_fma_f32 v[34:35], v[98:99], v[34:35], v[54:55]
	v_pk_fma_f32 v[52:53], v[96:97], v[32:33], v[52:53]
	v_pk_fma_f32 v[32:33], v[90:91], v[38:39], v[34:35]
	v_pk_fma_f32 v[34:35], v[88:89], v[36:37], v[52:53]
	v_add_u32_e32 v36, 0xfffffe10, v246
	ds_read_b128 v[36:39], v36
	ds_read_b128 v[52:55], v244 offset:2576
	v_mov_b32_dpp v42, v42 row_ror:1 row_mask:0xf bank_mask:0xf
	v_mov_b32_dpp v43, v43 row_ror:1 row_mask:0xf bank_mask:0xf
	v_pk_fma_f32 v[40:41], v[90:91], v[42:43], v[40:41]
	v_pk_fma_f32 v[42:43], v[88:89], v[136:137], v[140:141]
	s_waitcnt lgkmcnt(0)
	v_pk_mul_f32 v[90:91], v[172:173], v[52:53]
	v_cndmask_b32_e32 v52, v20, v28, vcc
	v_cndmask_b32_e32 v53, v21, v29, vcc
	v_pk_mul_f32 v[36:37], v[170:171], v[36:37]
	v_pk_mul_f32 v[88:89], v[168:169], v[54:55]
	v_mov_b32_dpp v52, v52 row_ror:15 row_mask:0xf bank_mask:0xf
	v_mov_b32_dpp v53, v53 row_ror:15 row_mask:0xf bank_mask:0xf
	v_cndmask_b32_e32 v54, v22, v30, vcc
	v_cndmask_b32_e32 v55, v23, v31, vcc
	v_pk_mul_f32 v[38:39], v[166:167], v[38:39]
	v_cndmask_b32_e64 v36, v20, v36, s[6:7]
	v_cndmask_b32_e64 v37, v21, v37, s[6:7]
	v_mov_b32_dpp v54, v54 row_ror:15 row_mask:0xf bank_mask:0xf
	v_mov_b32_dpp v55, v55 row_ror:15 row_mask:0xf bank_mask:0xf
	s_waitcnt vmcnt(0)
	v_pk_fma_f32 v[52:53], v[72:73], v[52:53], v[76:77]
	v_mov_b32_dpp v36, v36 row_ror:1 row_mask:0xf bank_mask:0xf
	v_mov_b32_dpp v37, v37 row_ror:1 row_mask:0xf bank_mask:0xf
	v_cndmask_b32_e64 v38, v22, v38, s[6:7]
	v_cndmask_b32_e64 v39, v23, v39, s[6:7]
	v_pk_fma_f32 v[54:55], v[74:75], v[54:55], v[78:79]
	v_pk_fma_f32 v[96:97], v[68:69], v[20:21], v[52:53]
	v_mov_b32_dpp v38, v38 row_ror:1 row_mask:0xf bank_mask:0xf
	v_mov_b32_dpp v39, v39 row_ror:1 row_mask:0xf bank_mask:0xf
	v_pk_fma_f32 v[52:53], v[70:71], v[22:23], v[54:55]
	v_pk_fma_f32 v[54:55], v[64:65], v[36:37], v[96:97]
	v_cndmask_b32_e32 v36, v28, v24, vcc
	v_cndmask_b32_e32 v37, v29, v25, vcc
	v_pk_fma_f32 v[52:53], v[66:67], v[38:39], v[52:53]
	v_mov_b32_dpp v36, v36 row_ror:15 row_mask:0xf bank_mask:0xf
	v_mov_b32_dpp v37, v37 row_ror:15 row_mask:0xf bank_mask:0xf
	v_cndmask_b32_e32 v38, v30, v26, vcc
	v_cndmask_b32_e32 v39, v31, v27, vcc
	v_cndmask_b32_e64 v20, v28, v20, s[6:7]
	v_cndmask_b32_e64 v21, v29, v21, s[6:7]
	v_mov_b32_dpp v38, v38 row_ror:15 row_mask:0xf bank_mask:0xf
	v_mov_b32_dpp v39, v39 row_ror:15 row_mask:0xf bank_mask:0xf
	v_pk_fma_f32 v[36:37], v[72:73], v[36:37], v[76:77]
	v_mov_b32_dpp v20, v20 row_ror:1 row_mask:0xf bank_mask:0xf
	v_mov_b32_dpp v21, v21 row_ror:1 row_mask:0xf bank_mask:0xf
	v_cndmask_b32_e64 v22, v30, v22, s[6:7]
	v_cndmask_b32_e64 v23, v31, v23, s[6:7]
	v_pk_fma_f32 v[38:39], v[74:75], v[38:39], v[78:79]
	v_pk_fma_f32 v[96:97], v[68:69], v[28:29], v[36:37]
	v_mov_b32_dpp v22, v22 row_ror:1 row_mask:0xf bank_mask:0xf
	v_mov_b32_dpp v23, v23 row_ror:1 row_mask:0xf bank_mask:0xf
	v_pk_fma_f32 v[36:37], v[70:71], v[30:31], v[38:39]
	v_pk_fma_f32 v[38:39], v[64:65], v[20:21], v[96:97]
	v_cndmask_b32_e32 v21, v24, v16, vcc
	v_pk_fma_f32 v[36:37], v[66:67], v[22:23], v[36:37]
	v_cndmask_b32_e64 v20, v24, v28, s[6:7]
	v_mov_b32_dpp v22, v21 row_ror:15 row_mask:0xf bank_mask:0xf
	v_cndmask_b32_e64 v21, v25, v29, s[6:7]
	v_cndmask_b32_e32 v29, v26, v18, vcc
	v_cndmask_b32_e32 v23, v25, v17, vcc
	v_cndmask_b32_e64 v28, v26, v30, s[6:7]
	v_mov_b32_dpp v30, v29 row_ror:15 row_mask:0xf bank_mask:0xf
	v_cndmask_b32_e64 v29, v27, v31, s[6:7]
	v_cndmask_b32_e32 v31, v27, v19, vcc
	v_mov_b32_dpp v23, v23 row_ror:15 row_mask:0xf bank_mask:0xf
	v_pk_fma_f32 v[22:23], v[72:73], v[22:23], v[76:77]
	v_mov_b32_dpp v31, v31 row_ror:15 row_mask:0xf bank_mask:0xf
	v_pk_fma_f32 v[30:31], v[74:75], v[30:31], v[78:79]
	v_mov_b32_dpp v20, v20 row_ror:1 row_mask:0xf bank_mask:0xf
	v_mov_b32_dpp v21, v21 row_ror:1 row_mask:0xf bank_mask:0xf
	v_mov_b32_dpp v28, v28 row_ror:1 row_mask:0xf bank_mask:0xf
	v_mov_b32_dpp v29, v29 row_ror:1 row_mask:0xf bank_mask:0xf
	v_pk_fma_f32 v[22:23], v[68:69], v[24:25], v[22:23]
	v_pk_fma_f32 v[30:31], v[70:71], v[26:27], v[30:31]
	v_cndmask_b32_e32 v137, v6, v2, vcc
	v_pk_fma_f32 v[28:29], v[66:67], v[28:29], v[30:31]
	v_pk_fma_f32 v[30:31], v[64:65], v[20:21], v[22:23]
	v_cndmask_b32_e32 v21, v16, v90, vcc
	v_cndmask_b32_e32 v23, v17, v91, vcc
	v_cndmask_b32_e64 v20, v16, v24, s[6:7]
	v_mov_b32_dpp v22, v21 row_ror:15 row_mask:0xf bank_mask:0xf
	v_cndmask_b32_e64 v21, v17, v25, s[6:7]
	v_cndmask_b32_e32 v25, v18, v88, vcc
	v_mov_b32_dpp v23, v23 row_ror:15 row_mask:0xf bank_mask:0xf
	v_cndmask_b32_e64 v24, v18, v26, s[6:7]
	v_mov_b32_dpp v26, v25 row_ror:15 row_mask:0xf bank_mask:0xf
	v_cndmask_b32_e64 v25, v19, v27, s[6:7]
	v_cndmask_b32_e32 v27, v19, v89, vcc
	v_pk_fma_f32 v[22:23], v[72:73], v[22:23], v[76:77]
	v_mov_b32_dpp v20, v20 row_ror:1 row_mask:0xf bank_mask:0xf
	v_mov_b32_dpp v27, v27 row_ror:15 row_mask:0xf bank_mask:0xf
	v_mov_b32_dpp v21, v21 row_ror:1 row_mask:0xf bank_mask:0xf
	v_pk_fma_f32 v[26:27], v[74:75], v[26:27], v[78:79]
	v_pk_fma_f32 v[16:17], v[68:69], v[16:17], v[22:23]
	v_mov_b32_dpp v24, v24 row_ror:1 row_mask:0xf bank_mask:0xf
	v_mov_b32_dpp v25, v25 row_ror:1 row_mask:0xf bank_mask:0xf
	v_pk_fma_f32 v[18:19], v[70:71], v[18:19], v[26:27]
	v_pk_fma_f32 v[26:27], v[64:65], v[20:21], v[16:17]
	v_add_u32_e32 v16, 0xfffffe10, v245
	v_pk_fma_f32 v[24:25], v[66:67], v[24:25], v[18:19]
	ds_read_b128 v[20:23], v16
	ds_read_b128 v[16:19], v243 offset:2576
	v_cndmask_b32_e32 v139, v7, v3, vcc
	v_mov_b32_dpp v138, v137 row_ror:15 row_mask:0xf bank_mask:0xf
	v_cndmask_b32_e64 v136, v6, v14, s[6:7]
	s_waitcnt lgkmcnt(1)
	v_pk_mul_f32 v[20:21], v[180:181], v[20:21]
	v_pk_mul_f32 v[22:23], v[174:175], v[22:23]
	v_cndmask_b32_e64 v20, v8, v20, s[6:7]
	s_waitcnt lgkmcnt(0)
	v_pk_mul_f32 v[18:19], v[178:179], v[18:19]
	v_pk_mul_f32 v[16:17], v[182:183], v[16:17]
	v_mov_b32_dpp v88, v20 row_ror:1 row_mask:0xf bank_mask:0xf
	v_cndmask_b32_e32 v20, v8, v12, vcc
	v_mov_b32_dpp v139, v139 row_ror:15 row_mask:0xf bank_mask:0xf
	v_cndmask_b32_e32 v16, v0, v16, vcc
	v_mov_b32_dpp v90, v20 row_ror:15 row_mask:0xf bank_mask:0xf
	v_cndmask_b32_e64 v20, v9, v21, s[6:7]
	v_cndmask_b32_e64 v21, v5, v13, s[6:7]
	v_cndmask_b32_e32 v17, v1, v17, vcc
	v_mov_b32_dpp v89, v20 row_ror:1 row_mask:0xf bank_mask:0xf
	v_cndmask_b32_e32 v20, v9, v13, vcc
	v_cndmask_b32_e32 v18, v2, v18, vcc
	v_cndmask_b32_e32 v19, v3, v19, vcc
	v_mov_b32_dpp v91, v20 row_ror:15 row_mask:0xf bank_mask:0xf
	v_cndmask_b32_e64 v20, v10, v22, s[6:7]
	v_pk_fma_f32 v[138:139], v[74:75], v[138:139], v[78:79]
	v_mov_b32_dpp v16, v16 row_ror:15 row_mask:0xf bank_mask:0xf
	v_mov_b32_dpp v96, v20 row_ror:1 row_mask:0xf bank_mask:0xf
	v_cndmask_b32_e32 v20, v10, v14, vcc
	v_mov_b32_dpp v17, v17 row_ror:15 row_mask:0xf bank_mask:0xf
	v_mov_b32_dpp v18, v18 row_ror:15 row_mask:0xf bank_mask:0xf
	v_mov_b32_dpp v98, v20 row_ror:15 row_mask:0xf bank_mask:0xf
	v_cndmask_b32_e64 v20, v11, v23, s[6:7]
	v_mov_b32_dpp v23, v21 row_ror:1 row_mask:0xf bank_mask:0xf
	v_cndmask_b32_e32 v21, v5, v1, vcc
	v_mov_b32_dpp v97, v20 row_ror:1 row_mask:0xf bank_mask:0xf
	v_cndmask_b32_e32 v20, v11, v15, vcc
	v_mov_b32_dpp v21, v21 row_ror:15 row_mask:0xf bank_mask:0xf
	v_mov_b32_dpp v19, v19 row_ror:15 row_mask:0xf bank_mask:0xf
	v_mov_b32_dpp v99, v20 row_ror:15 row_mask:0xf bank_mask:0xf
	v_cndmask_b32_e64 v20, v12, v8, s[6:7]
	v_cndmask_b32_e64 v137, v7, v15, s[6:7]
	v_pk_fma_f32 v[18:19], v[74:75], v[18:19], v[78:79]
	v_mov_b32_dpp v100, v20 row_ror:1 row_mask:0xf bank_mask:0xf
	v_cndmask_b32_e32 v20, v12, v4, vcc
	v_pk_fma_f32 v[16:17], v[72:73], v[16:17], v[76:77]
	v_pk_fma_f32 v[90:91], v[72:73], v[90:91], v[76:77]
	v_mov_b32_dpp v102, v20 row_ror:15 row_mask:0xf bank_mask:0xf
	v_cndmask_b32_e64 v20, v13, v9, s[6:7]
	v_pk_fma_f32 v[16:17], v[68:69], v[0:1], v[16:17]
	v_pk_fma_f32 v[98:99], v[74:75], v[98:99], v[78:79]
	v_mov_b32_dpp v101, v20 row_ror:1 row_mask:0xf bank_mask:0xf
	v_cndmask_b32_e32 v20, v13, v5, vcc
	v_pk_fma_f32 v[90:91], v[68:69], v[8:9], v[90:91]
	v_pk_fma_f32 v[8:9], v[70:71], v[10:11], v[98:99]
	v_mov_b32_dpp v103, v20 row_ror:15 row_mask:0xf bank_mask:0xf
	v_cndmask_b32_e64 v20, v14, v10, s[6:7]
	v_pk_fma_f32 v[102:103], v[72:73], v[102:103], v[76:77]
	v_mov_b32_dpp v136, v136 row_ror:1 row_mask:0xf bank_mask:0xf
	v_mov_b32_dpp v104, v20 row_ror:1 row_mask:0xf bank_mask:0xf
	v_cndmask_b32_e32 v20, v14, v6, vcc
	v_pk_fma_f32 v[102:103], v[68:69], v[12:13], v[102:103]
	v_mov_b32_dpp v137, v137 row_ror:1 row_mask:0xf bank_mask:0xf
	v_mov_b32_dpp v106, v20 row_ror:15 row_mask:0xf bank_mask:0xf
	v_cndmask_b32_e64 v20, v15, v11, s[6:7]
	v_pk_fma_f32 v[10:11], v[64:65], v[88:89], v[90:91]
	v_pk_fma_f32 v[8:9], v[66:67], v[96:97], v[8:9]
	v_mov_b32_dpp v105, v20 row_ror:1 row_mask:0xf bank_mask:0xf
	v_cndmask_b32_e32 v20, v15, v7, vcc
	s_nop 1
	v_mov_b32_dpp v107, v20 row_ror:15 row_mask:0xf bank_mask:0xf
	v_cndmask_b32_e64 v20, v4, v12, s[6:7]
	v_pk_fma_f32 v[106:107], v[74:75], v[106:107], v[78:79]
	s_nop 0
	v_mov_b32_dpp v22, v20 row_ror:1 row_mask:0xf bank_mask:0xf
	v_cndmask_b32_e32 v20, v4, v0, vcc
	v_pk_fma_f32 v[12:13], v[70:71], v[14:15], v[106:107]
	v_pk_fma_f32 v[14:15], v[64:65], v[100:101], v[102:103]
	v_mov_b32_dpp v20, v20 row_ror:15 row_mask:0xf bank_mask:0xf
	v_pk_fma_f32 v[20:21], v[72:73], v[20:21], v[76:77]
	v_pk_fma_f32 v[12:13], v[66:67], v[104:105], v[12:13]
	v_pk_fma_f32 v[140:141], v[68:69], v[4:5], v[20:21]
	v_pk_fma_f32 v[20:21], v[70:71], v[6:7], v[138:139]
	v_cndmask_b32_e64 v4, v0, v4, s[6:7]
	v_cndmask_b32_e64 v5, v1, v5, s[6:7]
	v_cndmask_b32_e64 v6, v2, v6, s[6:7]
	v_cndmask_b32_e64 v7, v3, v7, s[6:7]
	v_mov_b32_dpp v4, v4 row_ror:1 row_mask:0xf bank_mask:0xf
	v_mov_b32_dpp v5, v5 row_ror:1 row_mask:0xf bank_mask:0xf
	v_mov_b32_dpp v6, v6 row_ror:1 row_mask:0xf bank_mask:0xf
	v_mov_b32_dpp v7, v7 row_ror:1 row_mask:0xf bank_mask:0xf
	v_pk_fma_f32 v[2:3], v[70:71], v[2:3], v[18:19]
	v_pk_fma_f32 v[22:23], v[64:65], v[22:23], v[140:141]
	v_pk_fma_f32 v[0:1], v[66:67], v[6:7], v[2:3]
	v_pk_fma_f32 v[2:3], v[64:65], v[4:5], v[16:17]
	v_mul_f32_e32 v4, 0xbfb8aa3b, v204
	v_mul_f32_e32 v5, 0xbfb8aa3b, v205
	v_exp_f32_e32 v4, v4
	v_exp_f32_e32 v5, v5
	v_pk_fma_f32 v[20:21], v[66:67], v[136:137], v[20:21]
	s_lshl_b32 s6, s30, 8
	v_add_f32_e32 v4, 1.0, v4
	v_add_f32_e32 v5, 1.0, v5
	v_rcp_f32_e32 v4, v4
	v_rcp_f32_e32 v5, v5
	s_add_i32 s6, s6, s83
	v_mul_f32_e32 v17, 0xbfb8aa3b, v200
	v_add_u32_e32 v16, s6, v242
	v_pk_mul_f32 v[4:5], v[204:205], v[4:5]
	v_readlane_b32 s6, v253, 54
	v_pk_mul_f32 v[4:5], v[4:5], v[134:135]
	v_exp_f32_e32 v17, v17
	v_cvt_pk_bf16_f32 v64, v4, v5
	v_mul_f32_e32 v4, 0xbfb8aa3b, v202
	v_mul_f32_e32 v5, 0xbfb8aa3b, v203
	v_exp_f32_e32 v4, v4
	v_exp_f32_e32 v5, v5
	v_readlane_b32 s7, v253, 55
	v_lshlrev_b64 v[6:7], 1, v[188:189]
	v_add_f32_e32 v4, 1.0, v4
	v_add_f32_e32 v5, 1.0, v5
	v_rcp_f32_e32 v4, v4
	v_rcp_f32_e32 v5, v5
	v_add_f32_e32 v17, 1.0, v17
	s_andn2_b64 vcc, exec, s[4:5]
	v_pk_mul_f32 v[4:5], v[202:203], v[4:5]
	s_nop 0
	v_pk_mul_f32 v[4:5], v[4:5], v[132:133]
	s_nop 0
	v_cvt_pk_bf16_f32 v65, v4, v5
	v_mul_f32_e32 v4, 0xbfb8aa3b, v158
	v_mul_f32_e32 v5, 0xbfb8aa3b, v159
	v_exp_f32_e32 v4, v4
	v_exp_f32_e32 v5, v5
	v_add_f32_e32 v4, 1.0, v4
	v_add_f32_e32 v5, 1.0, v5
	v_rcp_f32_e32 v4, v4
	v_rcp_f32_e32 v5, v5
	s_nop 0
	v_pk_mul_f32 v[4:5], v[158:159], v[4:5]
	s_nop 0
	v_pk_mul_f32 v[4:5], v[4:5], v[54:55]
	s_nop 0
	v_cvt_pk_bf16_f32 v66, v4, v5
	v_mul_f32_e32 v4, 0xbfb8aa3b, v156
	v_mul_f32_e32 v5, 0xbfb8aa3b, v157
	v_exp_f32_e32 v4, v4
	v_exp_f32_e32 v5, v5
	v_add_f32_e32 v4, 1.0, v4
	v_add_f32_e32 v5, 1.0, v5
	v_rcp_f32_e32 v4, v4
	v_rcp_f32_e32 v5, v5
	s_nop 0
	v_pk_mul_f32 v[4:5], v[156:157], v[4:5]
	s_nop 0
	v_pk_mul_f32 v[4:5], v[4:5], v[52:53]
	s_nop 0
	v_cvt_pk_bf16_f32 v67, v4, v5
	v_mov_b64_e32 v[4:5], s[6:7]
	v_mad_i64_i32 v[18:19], s[6:7], v16, s10, v[4:5]
	v_lshl_add_u64 v[18:19], v[18:19], 0, v[6:7]
	global_store_dwordx4 v[18:19], v[64:67], off
	v_rcp_f32_e32 v18, v17
	v_mul_f32_e32 v17, 0xbfb8aa3b, v201
	v_exp_f32_e32 v17, v17
	s_nop 0
	v_add_f32_e32 v17, 1.0, v17
	v_rcp_f32_e32 v19, v17
	v_mul_f32_e32 v17, 0xbfb8aa3b, v198
	v_exp_f32_e32 v17, v17
	v_pk_mul_f32 v[18:19], v[200:201], v[18:19]
	s_nop 0
	v_pk_mul_f32 v[18:19], v[18:19], v[130:131]
	v_add_f32_e32 v17, 1.0, v17
	v_cvt_pk_bf16_f32 v52, v18, v19
	v_rcp_f32_e32 v18, v17
	v_mul_f32_e32 v17, 0xbfb8aa3b, v199
	v_exp_f32_e32 v17, v17
	s_nop 0
	v_add_f32_e32 v17, 1.0, v17
	v_rcp_f32_e32 v19, v17
	v_mul_f32_e32 v17, 0xbfb8aa3b, v150
	v_exp_f32_e32 v17, v17
	v_pk_mul_f32 v[18:19], v[198:199], v[18:19]
	s_nop 0
	v_pk_mul_f32 v[18:19], v[18:19], v[128:129]
	v_add_f32_e32 v17, 1.0, v17
	v_cvt_pk_bf16_f32 v53, v18, v19
	v_rcp_f32_e32 v18, v17
	v_mul_f32_e32 v17, 0xbfb8aa3b, v151
	v_exp_f32_e32 v17, v17
	s_nop 0
	v_add_f32_e32 v17, 1.0, v17
	v_rcp_f32_e32 v19, v17
	v_mul_f32_e32 v17, 0xbfb8aa3b, v148
	v_exp_f32_e32 v17, v17
	v_pk_mul_f32 v[18:19], v[150:151], v[18:19]
	s_nop 0
	v_pk_mul_f32 v[18:19], v[18:19], v[38:39]
	v_add_f32_e32 v17, 1.0, v17
	v_cvt_pk_bf16_f32 v54, v18, v19
	v_rcp_f32_e32 v18, v17
	v_mul_f32_e32 v17, 0xbfb8aa3b, v149
	v_exp_f32_e32 v17, v17
	s_nop 0
	v_add_f32_e32 v17, 1.0, v17
	v_rcp_f32_e32 v19, v17
	v_add_u32_e32 v17, 16, v16
	v_pk_mul_f32 v[18:19], v[148:149], v[18:19]
	s_nop 0
	v_pk_mul_f32 v[18:19], v[18:19], v[36:37]
	s_nop 0
	v_cvt_pk_bf16_f32 v55, v18, v19
	v_mad_i64_i32 v[18:19], s[6:7], v17, s10, v[4:5]
	v_mul_f32_e32 v17, 0xbfb8aa3b, v196
	v_exp_f32_e32 v17, v17
	v_lshl_add_u64 v[18:19], v[18:19], 0, v[6:7]
	global_store_dwordx4 v[18:19], v[52:55], off
	v_add_f32_e32 v17, 1.0, v17
	v_rcp_f32_e32 v18, v17
	v_mul_f32_e32 v17, 0xbfb8aa3b, v197
	v_exp_f32_e32 v17, v17
	s_nop 0
	v_add_f32_e32 v17, 1.0, v17
	v_rcp_f32_e32 v19, v17
	v_mul_f32_e32 v17, 0xbfb8aa3b, v194
	v_exp_f32_e32 v17, v17
	v_pk_mul_f32 v[18:19], v[196:197], v[18:19]
	s_nop 0
	v_pk_mul_f32 v[18:19], v[18:19], v[62:63]
	v_add_f32_e32 v17, 1.0, v17
	v_cvt_pk_bf16_f32 v36, v18, v19
	v_rcp_f32_e32 v18, v17
	v_mul_f32_e32 v17, 0xbfb8aa3b, v195
	v_exp_f32_e32 v17, v17
	s_nop 0
	v_add_f32_e32 v17, 1.0, v17
	v_rcp_f32_e32 v19, v17
	v_mul_f32_e32 v17, 0xbfb8aa3b, v110
	v_exp_f32_e32 v17, v17
	v_pk_mul_f32 v[18:19], v[194:195], v[18:19]
	s_nop 0
	v_pk_mul_f32 v[18:19], v[18:19], v[60:61]
	v_add_f32_e32 v17, 1.0, v17
	v_cvt_pk_bf16_f32 v37, v18, v19
	v_rcp_f32_e32 v18, v17
	v_mul_f32_e32 v17, 0xbfb8aa3b, v111
	v_exp_f32_e32 v17, v17
	s_nop 0
	v_add_f32_e32 v17, 1.0, v17
	v_rcp_f32_e32 v19, v17
	v_mul_f32_e32 v17, 0xbfb8aa3b, v108
	v_exp_f32_e32 v17, v17
	v_pk_mul_f32 v[18:19], v[110:111], v[18:19]
	s_nop 0
	v_pk_mul_f32 v[18:19], v[18:19], v[30:31]
	v_add_f32_e32 v17, 1.0, v17
	v_cvt_pk_bf16_f32 v38, v18, v19
	v_rcp_f32_e32 v18, v17
	v_mul_f32_e32 v17, 0xbfb8aa3b, v109
	v_exp_f32_e32 v17, v17
	s_nop 0
	v_add_f32_e32 v17, 1.0, v17
	v_rcp_f32_e32 v19, v17
	v_add_u32_e32 v17, 32, v16
	v_pk_mul_f32 v[18:19], v[108:109], v[18:19]
	s_nop 0
	v_pk_mul_f32 v[18:19], v[18:19], v[28:29]
	s_nop 0
	v_cvt_pk_bf16_f32 v39, v18, v19
	v_mad_i64_i32 v[18:19], s[6:7], v17, s10, v[4:5]
	v_mul_f32_e32 v17, 0xbfb8aa3b, v192
	v_exp_f32_e32 v17, v17
	v_lshl_add_u64 v[18:19], v[18:19], 0, v[6:7]
	global_store_dwordx4 v[18:19], v[36:39], off
	v_add_f32_e32 v17, 1.0, v17
	v_rcp_f32_e32 v18, v17
	v_mul_f32_e32 v17, 0xbfb8aa3b, v193
	v_exp_f32_e32 v17, v17
	s_nop 0
	v_add_f32_e32 v17, 1.0, v17
	v_rcp_f32_e32 v19, v17
	v_mul_f32_e32 v17, 0xbfb8aa3b, v190
	v_exp_f32_e32 v17, v17
	v_pk_mul_f32 v[18:19], v[192:193], v[18:19]
	s_nop 0
	v_pk_mul_f32 v[18:19], v[18:19], v[58:59]
	v_add_f32_e32 v17, 1.0, v17
	v_cvt_pk_bf16_f32 v28, v18, v19
	v_rcp_f32_e32 v18, v17
	v_mul_f32_e32 v17, 0xbfb8aa3b, v191
	v_exp_f32_e32 v17, v17
	s_nop 0
	v_add_f32_e32 v17, 1.0, v17
	v_rcp_f32_e32 v19, v17
	v_mul_f32_e32 v17, 0xbfb8aa3b, v94
	v_exp_f32_e32 v17, v17
	v_pk_mul_f32 v[18:19], v[190:191], v[18:19]
	s_nop 0
	v_pk_mul_f32 v[18:19], v[18:19], v[56:57]
	v_add_f32_e32 v17, 1.0, v17
	v_cvt_pk_bf16_f32 v29, v18, v19
	v_rcp_f32_e32 v18, v17
	v_mul_f32_e32 v17, 0xbfb8aa3b, v95
	v_exp_f32_e32 v17, v17
	s_nop 0
	v_add_f32_e32 v17, 1.0, v17
	v_rcp_f32_e32 v19, v17
	v_mul_f32_e32 v17, 0xbfb8aa3b, v92
	v_exp_f32_e32 v17, v17
	v_pk_mul_f32 v[18:19], v[94:95], v[18:19]
	s_nop 0
	v_pk_mul_f32 v[18:19], v[18:19], v[26:27]
	v_add_f32_e32 v17, 1.0, v17
	v_cvt_pk_bf16_f32 v30, v18, v19
	v_rcp_f32_e32 v18, v17
	v_mul_f32_e32 v17, 0xbfb8aa3b, v93
	v_exp_f32_e32 v17, v17
	s_nop 0
	v_add_f32_e32 v17, 1.0, v17
	v_rcp_f32_e32 v19, v17
	v_add_u32_e32 v17, 48, v16
	v_pk_mul_f32 v[18:19], v[92:93], v[18:19]
	s_nop 0
	v_pk_mul_f32 v[18:19], v[18:19], v[24:25]
	s_nop 0
	v_cvt_pk_bf16_f32 v31, v18, v19
	v_mad_i64_i32 v[18:19], s[6:7], v17, s10, v[4:5]
	v_lshl_add_u64 v[18:19], v[18:19], 0, v[6:7]
	global_store_dwordx4 v[18:19], v[28:31], off
	v_mul_f32_e32 v18, 0xbfb8aa3b, v126
	v_mul_f32_e32 v19, 0xbfb8aa3b, v127
	v_exp_f32_e32 v18, v18
	v_exp_f32_e32 v19, v19
	v_add_u32_e32 v17, 0x80, v16
	v_add_f32_e32 v18, 1.0, v18
	v_add_f32_e32 v19, 1.0, v19
	v_rcp_f32_e32 v18, v18
	v_rcp_f32_e32 v19, v19
	s_nop 0
	v_pk_mul_f32 v[18:19], v[126:127], v[18:19]
	s_nop 0
	v_pk_mul_f32 v[18:19], v[18:19], v[50:51]
	s_nop 0
	v_cvt_pk_bf16_f32 v24, v18, v19
	v_mul_f32_e32 v18, 0xbfb8aa3b, v124
	v_mul_f32_e32 v19, 0xbfb8aa3b, v125
	v_exp_f32_e32 v18, v18
	v_exp_f32_e32 v19, v19
	v_add_f32_e32 v18, 1.0, v18
	v_add_f32_e32 v19, 1.0, v19
	v_rcp_f32_e32 v18, v18
	v_rcp_f32_e32 v19, v19
	s_nop 0
	v_pk_mul_f32 v[18:19], v[124:125], v[18:19]
	s_nop 0
	v_pk_mul_f32 v[18:19], v[18:19], v[48:49]
	s_nop 0
	v_cvt_pk_bf16_f32 v25, v18, v19
	v_mul_f32_e32 v18, 0xbfb8aa3b, v154
	v_mul_f32_e32 v19, 0xbfb8aa3b, v155
	v_exp_f32_e32 v18, v18
	v_exp_f32_e32 v19, v19
	v_add_f32_e32 v18, 1.0, v18
	v_add_f32_e32 v19, 1.0, v19
	v_rcp_f32_e32 v18, v18
	v_rcp_f32_e32 v19, v19
	s_nop 0
	v_pk_mul_f32 v[18:19], v[154:155], v[18:19]
	s_nop 0
	v_pk_mul_f32 v[10:11], v[18:19], v[10:11]
	s_nop 0
	v_cvt_pk_bf16_f32 v26, v10, v11
	v_mul_f32_e32 v10, 0xbfb8aa3b, v152
	v_mul_f32_e32 v11, 0xbfb8aa3b, v153
	v_exp_f32_e32 v10, v10
	v_exp_f32_e32 v11, v11
	v_add_f32_e32 v10, 1.0, v10
	v_add_f32_e32 v11, 1.0, v11
	v_rcp_f32_e32 v10, v10
	v_rcp_f32_e32 v11, v11
	s_nop 0
	v_pk_mul_f32 v[10:11], v[152:153], v[10:11]
	s_nop 0
	v_pk_mul_f32 v[8:9], v[10:11], v[8:9]
	s_nop 0
	v_cvt_pk_bf16_f32 v27, v8, v9
	v_mad_i64_i32 v[8:9], s[6:7], v17, s10, v[4:5]
	v_lshl_add_u64 v[8:9], v[8:9], 0, v[6:7]
	global_store_dwordx4 v[8:9], v[24:27], off
	v_mul_f32_e32 v8, 0xbfb8aa3b, v122
	v_mul_f32_e32 v9, 0xbfb8aa3b, v123
	v_exp_f32_e32 v8, v8
	v_exp_f32_e32 v9, v9
	v_add_f32_e32 v8, 1.0, v8
	v_add_f32_e32 v9, 1.0, v9
	v_rcp_f32_e32 v8, v8
	v_rcp_f32_e32 v9, v9
	s_nop 0
	v_pk_mul_f32 v[8:9], v[122:123], v[8:9]
	s_nop 0
	v_pk_mul_f32 v[8:9], v[8:9], v[46:47]
	s_nop 0
	v_cvt_pk_bf16_f32 v8, v8, v9
	v_mul_f32_e32 v9, 0xbfb8aa3b, v120
	v_exp_f32_e32 v9, v9
	s_nop 0
	v_add_f32_e32 v9, 1.0, v9
	v_rcp_f32_e32 v10, v9
	v_mul_f32_e32 v9, 0xbfb8aa3b, v121
	v_exp_f32_e32 v9, v9
	s_nop 0
	v_add_f32_e32 v9, 1.0, v9
	v_rcp_f32_e32 v11, v9
	s_nop 0
	v_pk_mul_f32 v[10:11], v[120:121], v[10:11]
	s_nop 0
	v_pk_mul_f32 v[10:11], v[10:11], v[44:45]
	s_nop 0
	v_cvt_pk_bf16_f32 v9, v10, v11
	v_mul_f32_e32 v10, 0xbfb8aa3b, v146
	v_mul_f32_e32 v11, 0xbfb8aa3b, v147
	v_exp_f32_e32 v10, v10
	v_exp_f32_e32 v11, v11
	v_add_f32_e32 v10, 1.0, v10
	v_add_f32_e32 v11, 1.0, v11
	v_rcp_f32_e32 v10, v10
	v_rcp_f32_e32 v11, v11
	s_nop 0
	v_pk_mul_f32 v[10:11], v[146:147], v[10:11]
	s_nop 0
	v_pk_mul_f32 v[10:11], v[10:11], v[14:15]
	s_nop 0
	v_cvt_pk_bf16_f32 v10, v10, v11
	v_mul_f32_e32 v11, 0xbfb8aa3b, v144
	v_exp_f32_e32 v11, v11
	s_nop 0
	v_add_f32_e32 v11, 1.0, v11
	v_rcp_f32_e32 v14, v11
	v_mul_f32_e32 v11, 0xbfb8aa3b, v145
	v_exp_f32_e32 v11, v11
	s_nop 0
	v_add_f32_e32 v11, 1.0, v11
	v_rcp_f32_e32 v15, v11
	s_nop 0
	v_pk_mul_f32 v[14:15], v[144:145], v[14:15]
	s_nop 0
	v_pk_mul_f32 v[12:13], v[14:15], v[12:13]
	s_nop 0
	v_cvt_pk_bf16_f32 v11, v12, v13
	v_add_u32_e32 v12, 0x90, v16
	v_mad_i64_i32 v[12:13], s[6:7], v12, s10, v[4:5]
	v_lshl_add_u64 v[12:13], v[12:13], 0, v[6:7]
	global_store_dwordx4 v[12:13], v[8:11], off
	s_nop 1
	v_mul_f32_e32 v8, 0xbfb8aa3b, v118
	v_mul_f32_e32 v9, 0xbfb8aa3b, v119
	v_exp_f32_e32 v8, v8
	v_exp_f32_e32 v9, v9
	v_add_f32_e32 v8, 1.0, v8
	v_add_f32_e32 v9, 1.0, v9
	v_rcp_f32_e32 v8, v8
	v_rcp_f32_e32 v9, v9
	s_nop 0
	v_pk_mul_f32 v[8:9], v[118:119], v[8:9]
	s_nop 0
	v_pk_mul_f32 v[8:9], v[8:9], v[42:43]
	s_nop 0
	v_cvt_pk_bf16_f32 v8, v8, v9
	v_mul_f32_e32 v9, 0xbfb8aa3b, v116
	v_exp_f32_e32 v9, v9
	s_nop 0
	v_add_f32_e32 v9, 1.0, v9
	v_rcp_f32_e32 v10, v9
	v_mul_f32_e32 v9, 0xbfb8aa3b, v117
	v_exp_f32_e32 v9, v9
	s_nop 0
	v_add_f32_e32 v9, 1.0, v9
	v_rcp_f32_e32 v11, v9
	s_nop 0
	v_pk_mul_f32 v[10:11], v[116:117], v[10:11]
	s_nop 0
	v_pk_mul_f32 v[10:11], v[10:11], v[40:41]
	s_nop 0
	v_cvt_pk_bf16_f32 v9, v10, v11
	v_mul_f32_e32 v10, 0xbfb8aa3b, v86
	v_mul_f32_e32 v11, 0xbfb8aa3b, v87
	v_exp_f32_e32 v10, v10
	v_exp_f32_e32 v11, v11
	v_add_f32_e32 v10, 1.0, v10
	v_add_f32_e32 v11, 1.0, v11
	v_rcp_f32_e32 v10, v10
	v_rcp_f32_e32 v11, v11
	s_nop 0
	v_pk_mul_f32 v[10:11], v[86:87], v[10:11]
	s_nop 0
	v_pk_mul_f32 v[10:11], v[10:11], v[22:23]
	s_nop 0
	v_cvt_pk_bf16_f32 v10, v10, v11
	v_mul_f32_e32 v11, 0xbfb8aa3b, v84
	v_exp_f32_e32 v11, v11
	s_nop 0
	v_add_f32_e32 v11, 1.0, v11
	v_rcp_f32_e32 v12, v11
	v_mul_f32_e32 v11, 0xbfb8aa3b, v85
	v_exp_f32_e32 v11, v11
	s_nop 0
	v_add_f32_e32 v11, 1.0, v11
	v_rcp_f32_e32 v13, v11
	s_nop 0
	v_pk_mul_f32 v[12:13], v[84:85], v[12:13]
	s_nop 0
	v_pk_mul_f32 v[12:13], v[12:13], v[20:21]
	s_nop 0
	v_cvt_pk_bf16_f32 v11, v12, v13
	v_add_u32_e32 v12, 0xa0, v16
	v_mad_i64_i32 v[12:13], s[6:7], v12, s10, v[4:5]
	v_lshl_add_u64 v[12:13], v[12:13], 0, v[6:7]
	global_store_dwordx4 v[12:13], v[8:11], off
	s_nop 1
	v_mul_f32_e32 v8, 0xbfb8aa3b, v114
	v_mul_f32_e32 v9, 0xbfb8aa3b, v115
	v_exp_f32_e32 v8, v8
	v_exp_f32_e32 v9, v9
	v_add_f32_e32 v8, 1.0, v8
	v_add_f32_e32 v9, 1.0, v9
	v_rcp_f32_e32 v8, v8
	v_rcp_f32_e32 v9, v9
	s_nop 0
	v_pk_mul_f32 v[8:9], v[114:115], v[8:9]
	s_nop 0
	v_pk_mul_f32 v[8:9], v[8:9], v[34:35]
	s_nop 0
	v_cvt_pk_bf16_f32 v8, v8, v9
	v_mul_f32_e32 v9, 0xbfb8aa3b, v112
	v_exp_f32_e32 v9, v9
	s_nop 0
	v_add_f32_e32 v9, 1.0, v9
	v_rcp_f32_e32 v10, v9
	v_mul_f32_e32 v9, 0xbfb8aa3b, v113
	v_exp_f32_e32 v9, v9
	s_nop 0
	v_add_f32_e32 v9, 1.0, v9
	v_rcp_f32_e32 v11, v9
	s_nop 0
	v_pk_mul_f32 v[10:11], v[112:113], v[10:11]
	s_nop 0
	v_pk_mul_f32 v[10:11], v[10:11], v[32:33]
	s_nop 0
	v_cvt_pk_bf16_f32 v9, v10, v11
	v_mul_f32_e32 v10, 0xbfb8aa3b, v82
	v_mul_f32_e32 v11, 0xbfb8aa3b, v83
	v_exp_f32_e32 v10, v10
	v_exp_f32_e32 v11, v11
	v_add_f32_e32 v10, 1.0, v10
	v_add_f32_e32 v11, 1.0, v11
	v_rcp_f32_e32 v10, v10
	v_rcp_f32_e32 v11, v11
	s_nop 0
	v_pk_mul_f32 v[10:11], v[82:83], v[10:11]
	s_nop 0
	v_pk_mul_f32 v[2:3], v[10:11], v[2:3]
	s_nop 0
	v_cvt_pk_bf16_f32 v10, v2, v3
	v_mul_f32_e32 v2, 0xbfb8aa3b, v80
	v_mul_f32_e32 v3, 0xbfb8aa3b, v81
	v_exp_f32_e32 v2, v2
	v_exp_f32_e32 v3, v3
	v_add_f32_e32 v2, 1.0, v2
	v_add_f32_e32 v3, 1.0, v3
	v_rcp_f32_e32 v2, v2
	v_rcp_f32_e32 v3, v3
	s_nop 0
	v_pk_mul_f32 v[2:3], v[80:81], v[2:3]
	s_nop 0
	v_pk_mul_f32 v[0:1], v[2:3], v[0:1]
	s_nop 0
	v_cvt_pk_bf16_f32 v11, v0, v1
	v_add_u32_e32 v0, 0xb0, v16
	v_mad_i64_i32 v[0:1], s[6:7], v0, s10, v[4:5]
	v_lshl_add_u64 v[0:1], v[0:1], 0, v[6:7]
	s_mov_b64 s[6:7], -1
	global_store_dwordx4 v[0:1], v[8:11], off
	s_cbranch_vccnz .LBB0_1378
	s_andn2_b64 vcc, exec, s[14:15]
	s_cbranch_vccnz .LBB0_1377
	s_barrier
	s_branch .LBB0_1377
